# h3AB
# baseline (speedup 1.0000x reference)
; DEVI float bf2f(u16 b) { return __uint_as_float((unsigned)b << 16); }
; DEVI unsigned cvtpk_nv(float lo, float hi) { unsigned r; asm("v_cvt_pk_bf16_f32 %0, %1, %2" : "=v"(r) : "v"(lo), "v"(hi)); return r; }
; template <int DQK, bool ALIBI>
; DEVI void attn_pass(const AttnArgs& a, f32x16 (&o)[4], const int tid_) {
;     ...
;   {
;     const u16* Qw = a.Q + (size_t)(a.qrow0 + (qrl < a.nq ? qrl : 0)) * a.ldq + hi * 8;
; #pragma unroll
;     for (int d0 = 0; d0 < DQK / 16; ++d0) qr[d0] = *(const bf16x8*)(Qw + d0 * 16);
;     if constexpr (DQK == 192) {
;       const float2* tb = a.ropetab + (size_t)(a.qpos0 + qrl) * 32 + hi * 8;
; #pragma unroll
;       for (int g = 0; g < 2; ++g) {
;         bf16x8 x1 = qr[8 + g], x2 = qr[10 + g]; unsigned w1[4], w2[4];
; #pragma unroll
;         for (int e = 0; e < 8; e += 2) {
;           const float2 c0 = tb[g * 16 + e], c1 = tb[g * 16 + e + 1];
;           const float a0 = bf2f((u16)x1[e]), b0 = bf2f((u16)x2[e]), a1 = bf2f((u16)x1[e + 1]), b1 = bf2f((u16)x2[e + 1]);
;           w1[e >> 1] = cvtpk_nv(a0 * c0.x - b0 * c0.y, a1 * c1.x - b1 * c1.y);
;           w2[e >> 1] = cvtpk_nv(b0 * c0.x + a0 * c0.y, b1 * c1.x + a1 * c1.y);
;         }
;         u32x4 v1 = {w1[0], w1[1], w1[2], w1[3]}, v2 = {w2[0], w2[1], w2[2], w2[3]};
;         qr[8 + g] = *reinterpret_cast<bf16x8*>(&v1); qr[10 + g] = *reinterpret_cast<bf16x8*>(&v2);
;       }
;     }
;   }
.LBB0_206:
	s_and_b64 vcc, exec, s[6:7]
	s_cbranch_vccz .LBB0_129
	v_lshlrev_b32_e32 v0, 1, v180
	v_add_u32_e32 v193, 0x200, v180
	v_bfe_u32 v2, v180, 2, 2
	v_lshrrev_b32_e32 v3, 1, v180
	v_and_b32_e32 v4, 0x60, v180
	v_lshlrev_b32_e32 v189, 3, v180
	v_ashrrev_i32_e32 v194, 4, v180
	v_lshlrev_b32_e32 v5, 4, v180
	s_cmp_lg_u32 s22, 0
	v_lshrrev_b32_e32 v185, 5, v180
	v_or_b32_e32 v182, v168, v181
	v_lshlrev_b32_e32 v148, 4, v179
	v_and_b32_e32 v190, 32, v0
	v_and_or_b32 v186, v3, 8, v2
	v_and_or_b32 v184, v189, 24, v4
	v_lshrrev_b32_e32 v195, 1, v194
	v_ashrrev_i32_e32 v187, 4, v193
	v_and_b32_e32 v191, 0xc0, v5
	v_and_b32_e32 v192, 0xfffffc00, v5
	v_and_b32_e32 v188, -16, v194
	s_cbranch_scc0 .LBB0_224
	s_mul_i32 s6, s14, 0xc0
	s_ashr_i32 s7, s6, 31
	s_lshl_b64 s[6:7], s[6:7], 1
	v_or_b32_e32 v183, v168, v181
	s_add_u32 s8, s76, s6
	v_cmp_gt_i32_e32 vcc, s27, v183
	s_addc_u32 s9, s77, s7
	v_mov_b64_e32 v[2:3], s[8:9]
	v_cndmask_b32_e32 v0, 0, v183, vcc
	v_add_u32_e32 v0, s19, v0
	v_mad_i64_i32 v[2:3], s[8:9], v0, s95, v[2:3]
	v_mov_b32_e32 v149, v1
	v_lshl_add_u64 v[50:51], v[2:3], 0, v[148:149]
	global_load_dwordx4 v[2:5], v[50:51], off offset:256
	global_load_dwordx4 v[6:9], v[50:51], off offset:320
	v_add_u32_e32 v10, s23, v183
	v_ashrrev_i32_e32 v11, 31, v10
	v_lshlrev_b64 v[10:11], 8, v[10:11]
	v_lshlrev_b32_e32 v0, 6, v179
	v_lshl_add_u64 v[10:11], s[74:75], 0, v[10:11]
	v_lshl_add_u64 v[46:47], v[10:11], 0, v[0:1]
	global_load_dwordx4 v[10:13], v[46:47], off
	global_load_dwordx4 v[14:17], v[46:47], off offset:16
	global_load_dwordx4 v[18:21], v[46:47], off offset:32
	global_load_dwordx4 v[22:25], v[46:47], off offset:48
	global_load_dwordx4 v[26:29], v[50:51], off offset:288
	global_load_dwordx4 v[30:33], v[50:51], off offset:352
	global_load_dwordx4 v[34:37], v[46:47], off offset:128
	global_load_dwordx4 v[38:41], v[46:47], off offset:144
	global_load_dwordx4 v[42:45], v[46:47], off offset:160
	s_nop 0
	global_load_dwordx4 v[46:49], v[46:47], off offset:176
	s_nop 0
	global_load_dwordx4 v[126:129], v[50:51], off
	global_load_dwordx4 v[122:125], v[50:51], off offset:32
	global_load_dwordx4 v[118:121], v[50:51], off offset:64
	global_load_dwordx4 v[114:117], v[50:51], off offset:96
	global_load_dwordx4 v[110:113], v[50:51], off offset:128
	global_load_dwordx4 v[106:109], v[50:51], off offset:160
	global_load_dwordx4 v[102:105], v[50:51], off offset:192
	global_load_dwordx4 v[98:101], v[50:51], off offset:224
	s_add_u32 s8, s78, s6
	s_addc_u32 s9, s79, s7
	s_lshl_b32 s6, s14, 7
	s_ashr_i32 s7, s6, 31
	s_lshl_b64 s[10:11], s[6:7], 1
	v_readlane_b32 s7, v253, 24
	s_add_u32 s10, s7, s10
	v_readlane_b32 s7, v253, 25
	s_addc_u32 s11, s7, s11
	s_mov_b32 s7, 0x2aaaaaab
	v_add_u32_e32 v197, 0, v192
	s_ashr_i32 s71, s70, 31
	s_mul_i32 s12, s70, 0xc00
	s_mul_hi_i32 s13, s70, 0xc00
	s_mov_b32 s3, 0
	v_mov_b32_e32 v151, v1
	v_mov_b32_e32 v153, v1
	v_mov_b32_e32 v155, v1
	v_mov_b32_e32 v157, v1
	v_mov_b32_e32 v149, 0
	v_mov_b32_e32 v199, 0xf149f2ca
	s_waitcnt vmcnt(19)
	v_lshlrev_b32_e32 v51, 16, v2
	s_waitcnt vmcnt(18)
	v_lshlrev_b32_e32 v50, 16, v6
	v_and_b32_e32 v53, 0xffff0000, v2
	v_and_b32_e32 v52, 0xffff0000, v6
	v_lshlrev_b32_e32 v55, 16, v3
	v_lshlrev_b32_e32 v54, 16, v7
	v_and_b32_e32 v3, 0xffff0000, v3
	v_and_b32_e32 v2, 0xffff0000, v7
	v_lshlrev_b32_e32 v7, 16, v4
	v_lshlrev_b32_e32 v6, 16, v8
	v_and_b32_e32 v57, 0xffff0000, v4
	v_and_b32_e32 v56, 0xffff0000, v8
	s_waitcnt vmcnt(17)
	v_pk_mul_f32 v[60:61], v[10:11], v[50:51] op_sel:[0,1] op_sel_hi:[1,0]
	v_pk_mul_f32 v[10:11], v[10:11], v[50:51]
	v_pk_mul_f32 v[50:51], v[12:13], v[52:53] op_sel:[0,1] op_sel_hi:[1,0]
	v_pk_mul_f32 v[12:13], v[12:13], v[52:53]
	s_waitcnt vmcnt(16)
	v_pk_mul_f32 v[52:53], v[14:15], v[54:55] op_sel:[0,1] op_sel_hi:[1,0]
	v_pk_mul_f32 v[14:15], v[14:15], v[54:55]
	v_pk_mul_f32 v[54:55], v[16:17], v[2:3] op_sel:[0,1] op_sel_hi:[1,0]
	v_pk_mul_f32 v[2:3], v[16:17], v[2:3]
	s_waitcnt vmcnt(15)
	v_pk_mul_f32 v[16:17], v[18:19], v[6:7] op_sel:[0,1] op_sel_hi:[1,0]
	v_lshlrev_b32_e32 v59, 16, v5
	v_lshlrev_b32_e32 v58, 16, v9
	v_pk_mul_f32 v[6:7], v[18:19], v[6:7]
	v_pk_mul_f32 v[18:19], v[20:21], v[56:57] op_sel:[0,1] op_sel_hi:[1,0]
	v_add_f32_e32 v2, v2, v3
	v_sub_f32_e32 v3, v16, v17
	v_sub_f32_e32 v0, v60, v61
	v_add_f32_e32 v4, v11, v10
	v_add_f32_e32 v10, v12, v13
	v_add_f32_e32 v12, v14, v15
	v_add_f32_e32 v6, v6, v7
	v_sub_f32_e32 v7, v18, v19
	v_cvt_pk_bf16_f32 v131, v12, v2
	v_cvt_pk_bf16_f32 v136, v3, v7
	s_waitcnt vmcnt(14)
	v_pk_mul_f32 v[2:3], v[22:23], v[58:59] op_sel:[0,1] op_sel_hi:[1,0]
	v_pk_mul_f32 v[20:21], v[20:21], v[56:57]
	v_sub_f32_e32 v8, v50, v51
	v_cvt_pk_bf16_f32 v134, v0, v8
	v_sub_f32_e32 v0, v2, v3
	v_pk_mul_f32 v[2:3], v[22:23], v[58:59]
	v_add_f32_e32 v14, v20, v21
	v_cvt_pk_bf16_f32 v132, v6, v14
	v_add_f32_e32 v6, v2, v3
	v_and_b32_e32 v3, 0xffff0000, v5
	v_and_b32_e32 v2, 0xffff0000, v9
	v_cvt_pk_bf16_f32 v130, v4, v10
	v_pk_mul_f32 v[4:5], v[24:25], v[2:3] op_sel:[0,1] op_sel_hi:[1,0]
	v_pk_mul_f32 v[2:3], v[24:25], v[2:3]
	v_sub_f32_e32 v4, v4, v5
	v_cvt_pk_bf16_f32 v137, v0, v4
	v_add_f32_e32 v0, v2, v3
	s_waitcnt vmcnt(13)
	v_lshlrev_b32_e32 v3, 16, v26
	s_waitcnt vmcnt(12)
	v_lshlrev_b32_e32 v2, 16, v30
	s_waitcnt vmcnt(11)
	v_pk_mul_f32 v[4:5], v[34:35], v[2:3] op_sel:[0,1] op_sel_hi:[1,0]
	v_pk_mul_f32 v[2:3], v[34:35], v[2:3]
	v_cvt_pk_bf16_f32 v133, v6, v0
	v_sub_f32_e32 v0, v4, v5
	v_add_f32_e32 v6, v2, v3
	v_and_b32_e32 v3, 0xffff0000, v26
	v_and_b32_e32 v2, 0xffff0000, v30
	v_pk_mul_f32 v[4:5], v[36:37], v[2:3] op_sel:[0,1] op_sel_hi:[1,0]
	v_pk_mul_f32 v[2:3], v[36:37], v[2:3]
	v_sub_f32_e32 v4, v4, v5
	v_cvt_pk_bf16_f32 v142, v0, v4
	v_add_f32_e32 v0, v2, v3
	v_lshlrev_b32_e32 v3, 16, v27
	v_lshlrev_b32_e32 v2, 16, v31
	s_waitcnt vmcnt(10)
; #define WAIT_V(n) asm volatile("s_waitcnt vmcnt(%0)" ::"n"(n) : "memory")
; template <int DQK, bool ALIBI>
; DEVI void attn_pass(const AttnArgs& a, f32x16 (&o)[4], const int tid_) {
;     ...
;   unsigned koff[NKI], voff[2];
; #pragma unroll
;   for (int i = 0; i < NKI; ++i) { const int s = tid + i * 512; const int rr = s / KCH, cp = s % KCH, cc = cp ^ KKEY(rr); koff[i] = (unsigned)(rr * a.ldk + cc * 8) * 2u; }
; #pragma unroll
;   for (int i = 0; i < 2; ++i) { const int s = tid + i * 512; const int kk = (s >> 7) * 8 + ((s & 31) >> 2);
;     const int kr = (kk & ~0xC) | ((kk & 4) << 1) | ((kk & 8) >> 1), vc = ((s >> 5) & 3) * 32 + (s & 3) * 8; voff[i] = (unsigned)(kr * a.ldv + vc) * 2u; }
;     ...
;   int j_lo = 0, j_hi = NT - 2; bool keep_meta = true;
;   if constexpr (ALIBI) {
;     const float qlo = (float)a.qpos0, qhi = (float)(a.qpos0 + a.nq - 1);
;     j_lo = (int)fmaxf(ceilf((qlo - 79.f - a.dskip) * (1.f / 64.f)), 0.f);
;     j_hi = (int)fminf(floorf((a.dskip + qhi - 16.f) * (1.f / 64.f)), (float)(NT - 2));
;     keep_meta = (qlo - 15.f) <= a.dskip;
;   }
;   const int nreal = j_hi - j_lo + 1, cnt = nreal + (keep_meta ? 1 : 0);
;   auto tile_of = [&](int n) -> int { return n < nreal ? j_lo + n : NT - 1; };
;   GLDS_KV(0, tile_of(0)); WAIT_V(0); __syncthreads();
	v_pk_mul_f32 v[4:5], v[38:39], v[2:3] op_sel:[0,1] op_sel_hi:[1,0]
	v_pk_mul_f32 v[2:3], v[38:39], v[2:3]
	v_cvt_pk_bf16_f32 v138, v6, v0
	v_sub_f32_e32 v0, v4, v5
	v_add_f32_e32 v6, v2, v3
	v_and_b32_e32 v3, 0xffff0000, v27
	v_and_b32_e32 v2, 0xffff0000, v31
	v_pk_mul_f32 v[4:5], v[40:41], v[2:3] op_sel:[0,1] op_sel_hi:[1,0]
	v_pk_mul_f32 v[2:3], v[40:41], v[2:3]
	v_sub_f32_e32 v4, v4, v5
	v_cvt_pk_bf16_f32 v143, v0, v4
	v_add_f32_e32 v0, v2, v3
	v_lshlrev_b32_e32 v3, 16, v28
	v_lshlrev_b32_e32 v2, 16, v32
	s_waitcnt vmcnt(9)
	v_pk_mul_f32 v[4:5], v[42:43], v[2:3] op_sel:[0,1] op_sel_hi:[1,0]
	v_pk_mul_f32 v[2:3], v[42:43], v[2:3]
	v_cvt_pk_bf16_f32 v139, v6, v0
	v_sub_f32_e32 v0, v4, v5
	v_add_f32_e32 v6, v2, v3
	v_and_b32_e32 v3, 0xffff0000, v28
	v_and_b32_e32 v2, 0xffff0000, v32
	v_pk_mul_f32 v[4:5], v[44:45], v[2:3] op_sel:[0,1] op_sel_hi:[1,0]
	v_pk_mul_f32 v[2:3], v[44:45], v[2:3]
	v_sub_f32_e32 v4, v4, v5
	v_cvt_pk_bf16_f32 v144, v0, v4
	v_add_f32_e32 v0, v2, v3
	v_lshlrev_b32_e32 v3, 16, v29
	v_lshlrev_b32_e32 v2, 16, v33
	s_waitcnt vmcnt(8)
	v_pk_mul_f32 v[4:5], v[46:47], v[2:3] op_sel:[0,1] op_sel_hi:[1,0]
	v_pk_mul_f32 v[2:3], v[46:47], v[2:3]
	v_cvt_pk_bf16_f32 v140, v6, v0
	v_sub_f32_e32 v0, v4, v5
	v_add_f32_e32 v6, v2, v3
	v_and_b32_e32 v3, 0xffff0000, v29
	v_and_b32_e32 v2, 0xffff0000, v33
	v_pk_mul_f32 v[4:5], v[48:49], v[2:3] op_sel:[0,1] op_sel_hi:[1,0]
	v_pk_mul_f32 v[2:3], v[48:49], v[2:3]
	v_sub_f32_e32 v4, v4, v5
	v_cvt_pk_bf16_f32 v145, v0, v4
	v_add_f32_e32 v0, v2, v3
	v_cvt_pk_bf16_f32 v141, v6, v0
	v_mul_hi_i32 v0, v180, s7
	v_lshrrev_b32_e32 v2, 31, v0
	v_ashrrev_i32_e32 v0, 2, v0
	v_add_u32_e32 v3, v0, v2
	v_mul_lo_u32 v0, v3, 24
	v_sub_u32_e32 v0, v180, v0
	v_lshrrev_b32_e32 v2, 1, v3
	v_bitop3_b32 v4, v2, v0, 7 bitop3:0x6c
	v_mul_hi_i32 v2, v193, s7
	v_lshrrev_b32_e32 v5, 31, v2
	v_ashrrev_i32_e32 v2, 2, v2
	v_add_u32_e32 v6, v2, v5
	v_mul_lo_u32 v2, v6, 24
	v_sub_u32_e32 v2, v193, v2
	v_lshrrev_b32_e32 v5, 1, v6
	v_bitop3_b32 v7, v5, v2, 7 bitop3:0x6c
	v_mul_lo_u32 v2, v6, s95
	v_lshl_add_u32 v150, v7, 4, v2
	v_add_u32_e32 v2, 0x400, v180
	v_mul_hi_i32 v5, v2, s7
	v_lshrrev_b32_e32 v8, 31, v5
	v_ashrrev_i32_e32 v5, 2, v5
	v_add_u32_e32 v8, v5, v8
	v_mul_lo_u32 v5, v8, 24
	v_sub_u32_e32 v2, v2, v5
	v_lshrrev_b32_e32 v5, 1, v8
	v_bitop3_b32 v9, v5, v2, 7 bitop3:0x6c
	v_mul_lo_u32 v2, v8, s95
	v_sub_f32_e32 v11, v52, v53
	v_lshl_add_u32 v152, v9, 4, v2
	v_and_b32_e32 v2, 0x1ffff0, v194
	v_and_b32_e32 v10, 4, v195
	v_sub_f32_e32 v13, v54, v55
	v_cvt_pk_bf16_f32 v135, v11, v13
	v_or3_b32 v5, v2, v186, v10
	v_lshlrev_b32_e32 v2, 1, v184
	v_lshrrev_b32_e32 v11, 1, v187
	v_lshl_or_b32 v154, v5, 11, v2
	v_and_b32_e32 v5, 0x1ffff0, v187
	v_and_b32_e32 v11, 4, v11
	v_or3_b32 v5, v5, v186, v11
	v_lshl_or_b32 v156, v5, 11, v2
	s_lshr_b32 s7, s66, 6
	v_add_u32_e32 v5, 0x8000, v197
	v_mul_lo_u32 v0, v3, s95
	s_add_u32 s12, s8, s12
	v_readfirstlane_b32 s34, v5
	v_add_u32_e32 v5, 0xa000, v197
	v_lshl_add_u32 v0, v4, 4, v0
	s_addc_u32 s13, s9, s13
	s_mov_b32 m0, s34
	v_readfirstlane_b32 s34, v5
	v_add_u32_e32 v5, 0xc000, v197
	global_load_lds_dwordx4 v0, s[12:13]
	s_mov_b32 m0, s34
	v_readfirstlane_b32 s34, v5
	global_load_lds_dwordx4 v150, s[12:13]
	s_mov_b32 m0, s34
	v_readfirstlane_b32 s34, v197
	global_load_lds_dwordx4 v152, s[12:13]
	s_lshl_b64 s[12:13], s[70:71], 11
	s_add_u32 s12, s10, s12
	v_add_u32_e32 v5, 0x2000, v197
	s_addc_u32 s13, s11, s13
	s_mov_b32 m0, s34
	v_readfirstlane_b32 s34, v5
	global_load_lds_dwordx4 v154, s[12:13]
	s_mov_b32 m0, s34
	v_min_i32_e32 v13, 15, v3
	global_load_lds_dwordx4 v156, s[12:13]
	v_or3_b32 v3, v10, v188, v186
	v_min_i32_e32 v10, 15, v3
	v_and_b32_e32 v3, -16, v187
	s_movk_i32 s12, 0x118
	v_bfe_u32 v12, v180, 1, 3
	v_or3_b32 v3, v186, v3, v11
	v_and_or_b32 v5, v189, s12, v190
	s_movk_i32 s12, 0x180
	s_cmp_lg_u32 0, -1
	v_min_i32_e32 v11, 15, v3
	v_bitop3_b32 v3, v185, v12, 1 bitop3:0x6c
	v_mad_u32_u24 v198, v181, s12, 0
	s_cselect_b32 s12, 0, 0
	v_lshlrev_b32_e32 v4, 3, v4
	v_lshlrev_b32_e32 v202, 4, v3
	v_bitop3_b32 v3, v179, v12, 2 bitop3:0x36
	v_add3_u32 v196, v191, s12, v5
	v_ashrrev_i32_e32 v5, 31, v4
	v_min_i32_e32 v14, 15, v6
	v_lshlrev_b32_e32 v6, 3, v7
	v_lshlrev_b32_e32 v203, 4, v3
	v_bitop3_b32 v3, v179, v12, 4 bitop3:0x36
	v_ashrrev_i32_e32 v7, 31, v6
	v_min_i32_e32 v15, 15, v8
	v_lshlrev_b32_e32 v8, 3, v9
	v_lshlrev_b32_e32 v200, 4, v3
	v_bitop3_b32 v3, v179, v12, 6 bitop3:0x36
	v_lshl_add_u64 v[4:5], v[4:5], 1, s[8:9]
	v_add_u32_e32 v12, s2, v13
	v_ashrrev_i32_e32 v9, 31, v8
	v_lshl_add_u64 v[6:7], v[6:7], 1, s[8:9]
	v_mad_i64_i32 v[158:159], s[12:13], v12, s95, v[4:5]
	v_add_u32_e32 v4, s2, v14
	v_lshl_add_u64 v[8:9], v[8:9], 1, s[8:9]
	v_mad_i64_i32 v[160:161], s[12:13], v4, s95, v[6:7]
	v_add_u32_e32 v4, s2, v15
	v_mad_i64_i32 v[162:163], s[12:13], v4, s95, v[8:9]
	v_add_u32_e32 v4, s2, v10
	v_lshlrev_b32_e32 v201, 4, v3
	v_mov_b32_e32 v3, v1
	v_ashrrev_i32_e32 v5, 31, v4
	v_lshl_add_u64 v[2:3], s[10:11], 0, v[2:3]
	v_lshlrev_b64 v[4:5], 11, v[4:5]
	v_lshl_add_u64 v[164:165], v[2:3], 0, v[4:5]
	v_add_u32_e32 v4, s2, v11
	v_ashrrev_i32_e32 v5, 31, v4
	s_waitcnt vmcnt(0)
	v_lshlrev_b64 v[4:5], 11, v[4:5]
	v_mov_b32_e32 v16, v1
	v_mov_b32_e32 v17, v1
	v_lshl_add_u64 v[166:167], v[2:3], 0, v[4:5]
	v_mov_b32_e32 v2, v1
	v_mov_b32_e32 v3, v1
	v_mov_b32_e32 v4, v1
	v_mov_b32_e32 v5, v1
	v_mov_b32_e32 v6, v1
	v_mov_b32_e32 v7, v1
	v_mov_b32_e32 v8, v1
	v_mov_b32_e32 v9, v1
	v_mov_b32_e32 v10, v1
	v_mov_b32_e32 v11, v1
	v_mov_b32_e32 v12, v1
	v_mov_b32_e32 v13, v1
	v_mov_b32_e32 v14, v1
	v_mov_b32_e32 v15, v1
	v_mov_b64_e32 v[32:33], v[16:17]
	v_mov_b64_e32 v[48:49], v[16:17]
	v_mov_b64_e32 v[64:65], v[16:17]
	s_add_i32 s12, s70, 64
	v_mov_b64_e32 v[30:31], v[14:15]
	v_mov_b64_e32 v[28:29], v[12:13]
	v_mov_b64_e32 v[26:27], v[10:11]
	v_mov_b64_e32 v[24:25], v[8:9]
	v_mov_b64_e32 v[22:23], v[6:7]
	v_mov_b64_e32 v[20:21], v[4:5]
	v_mov_b64_e32 v[18:19], v[2:3]
	v_mov_b64_e32 v[46:47], v[14:15]
	v_mov_b64_e32 v[44:45], v[12:13]
	v_mov_b64_e32 v[42:43], v[10:11]
	v_mov_b64_e32 v[40:41], v[8:9]
	v_mov_b64_e32 v[38:39], v[6:7]
	v_mov_b64_e32 v[36:37], v[4:5]
	v_mov_b64_e32 v[34:35], v[2:3]
	v_mov_b64_e32 v[62:63], v[14:15]
	v_mov_b64_e32 v[60:61], v[12:13]
	v_mov_b64_e32 v[58:59], v[10:11]
	v_mov_b64_e32 v[56:57], v[8:9]
	v_mov_b64_e32 v[54:55], v[6:7]
	v_mov_b64_e32 v[52:53], v[4:5]
	v_mov_b64_e32 v[50:51], v[2:3]
	s_waitcnt vmcnt(0) lgkmcnt(0)
	s_barrier
	s_branch .LBB0_211
.LBB0_210:
	s_or_b64 exec, exec, s[34:35]
	s_waitcnt vmcnt(0)
	s_add_i32 s12, s12, 64
	s_cmp_eq_u32 s7, s3
	s_waitcnt vmcnt(0) lgkmcnt(0)
	s_barrier
	s_cbranch_scc1 .LBB0_219

; #define SBAR() __builtin_amdgcn_sched_barrier(0)
; template <bool ALIBI, bool LAST>
; DEVI void softmax_tile(f32x16& p0, f32x16& p1, const float C, const float nslope2, const float dbase, float& m_reg, float& l_reg, float& alpha,
;                        bf16x8& pa0, bf16x8& pa1, bf16x8& pa2, bf16x8& pa3) {
;     ...
;   float pmax = p0[0];
; #pragma unroll
;   for (int r = 1; r < 16; ++r) pmax = fmaxf(pmax, p0[r]);
;   if constexpr (!LAST) {
; #pragma unroll
;     for (int r = 0; r < 16; ++r) pmax = fmaxf(pmax, p1[r]);
;   }
;   { auto rr = __builtin_amdgcn_permlane32_swap(__float_as_uint(pmax), __float_as_uint(pmax), false, false);
;     pmax = fmaxf(__uint_as_float(rr[0]), __uint_as_float(rr[1])); }
;   const float THRU = 8.f * LOG2E / C;
;   const float CU = C;
;   if (__builtin_expect(__all(pmax - m_reg <= THRU), 1)) { alpha = 1.f; }
;   else { float mn = fmaxf(m_reg, pmax); alpha = __builtin_amdgcn_exp2f((m_reg - mn) * CU); m_reg = mn; }
; template <int DQK, bool ALIBI>
; DEVI void attn_pass(const AttnArgs& a, f32x16 (&o)[4], const int tid_) {
;     ...
;       const unsigned char* Ks = K_lds + buf * SHM_K + r32 * KPITCH;
;       const int key = KKEY(r32);
;     ...
;       if constexpr (DQK == 128 || DQK == 64 || DQK == 192) {
;         constexpr int NG4 = DQK / 64;
;         bf16x8 ka[4][2], kb[4][2];
; #pragma unroll
;         for (int s = 0; s < 4; ++s) { ka[s][0] = *(const bf16x8*)(Ks + KCB(s)); ka[s][1] = *(const bf16x8*)(Ks + 32 * KPITCH + KCB(s)); }
;         SBAR();
; #pragma unroll
;         for (int g = 0; g < NG4; ++g) {
;           if (g + 1 < NG4) {
; #pragma unroll
;             for (int s = 0; s < 4; ++s) { const int d1 = (g + 1) * 4 + s;
;               if (g & 1) { ka[s][0] = *(const bf16x8*)(Ks + KCB(d1)); ka[s][1] = *(const bf16x8*)(Ks + 32 * KPITCH + KCB(d1)); }
;               else       { kb[s][0] = *(const bf16x8*)(Ks + KCB(d1)); kb[s][1] = *(const bf16x8*)(Ks + 32 * KPITCH + KCB(d1)); } }
;           }
; #pragma unroll
;           for (int s = 0; s < 4; ++s) { const int d0 = g * 4 + s;
;             p0 = __builtin_amdgcn_mfma_f32_32x32x16_bf16((g & 1) ? kb[s][0] : ka[s][0], qr[d0], p0, 0, 0, 0);
;             p1 = __builtin_amdgcn_mfma_f32_32x32x16_bf16((g & 1) ? kb[s][1] : ka[s][1], qr[d0], p1, 0, 0, 0); }
;           SBAR();
;         }
.LBB0_216:
	s_and_saveexec_b64 s[34:35], s[4:5]
	s_cbranch_execz .LBB0_210
	s_mul_i32 s13, s42, 0x6000
	v_add_u32_e32 v74, s13, v198
	v_add_u32_e32 v168, v74, v202
	v_add_u32_e32 v169, v74, v203
	v_add_u32_e32 v240, v74, v200
	v_add_u32_e32 v241, v74, v201
	ds_read_b128 v[66:69], v168 offset:32768
	ds_read_b128 v[70:73], v168 offset:45056
	ds_read_b128 v[204:207], v169 offset:32768
	ds_read_b128 v[208:211], v169 offset:45056
	ds_read_b128 v[212:215], v240 offset:32768
	ds_read_b128 v[216:219], v240 offset:45056
	ds_read_b128 v[220:223], v241 offset:32768
	ds_read_b128 v[224:227], v241 offset:45056
	s_waitcnt lgkmcnt(0)
	v_mfma_f32_32x32x16_bf16 v[82:97], v[66:69], v[126:129], 0
	v_mfma_f32_32x32x16_bf16 v[66:81], v[70:73], v[126:129], 0
	v_mfma_f32_32x32x16_bf16 v[82:97], v[204:207], v[122:125], v[82:97]
	v_mfma_f32_32x32x16_bf16 v[66:81], v[208:211], v[122:125], v[66:81]
	v_mfma_f32_32x32x16_bf16 v[82:97], v[212:215], v[118:121], v[82:97]
	v_mfma_f32_32x32x16_bf16 v[66:81], v[216:219], v[118:121], v[66:81]
	v_mfma_f32_32x32x16_bf16 v[82:97], v[220:223], v[114:117], v[82:97]
	ds_read_b128 v[204:207], v168 offset:32896
	ds_read_b128 v[208:211], v168 offset:45184
	ds_read_b128 v[212:215], v169 offset:32896
	ds_read_b128 v[216:219], v169 offset:45184
	ds_read_b128 v[220:223], v240 offset:32896
	ds_read_b128 v[228:231], v240 offset:45184
	ds_read_b128 v[232:235], v241 offset:32896
	ds_read_b128 v[236:239], v241 offset:45184
	v_mfma_f32_32x32x16_bf16 v[66:81], v[224:227], v[114:117], v[66:81]
	s_waitcnt lgkmcnt(0)
	v_mfma_f32_32x32x16_bf16 v[82:97], v[204:207], v[110:113], v[82:97]
	v_mfma_f32_32x32x16_bf16 v[66:81], v[208:211], v[110:113], v[66:81]
	v_mfma_f32_32x32x16_bf16 v[82:97], v[212:215], v[106:109], v[82:97]
	v_mfma_f32_32x32x16_bf16 v[66:81], v[216:219], v[106:109], v[66:81]
	v_mfma_f32_32x32x16_bf16 v[82:97], v[220:223], v[102:105], v[82:97]
	v_mfma_f32_32x32x16_bf16 v[66:81], v[228:231], v[102:105], v[66:81]
	v_mfma_f32_32x32x16_bf16 v[82:97], v[232:235], v[98:101], v[82:97]
	ds_read_b128 v[204:207], v168 offset:33024
	ds_read_b128 v[208:211], v168 offset:45312
	ds_read_b128 v[212:215], v169 offset:33024
	ds_read_b128 v[216:219], v169 offset:45312
	ds_read_b128 v[220:223], v240 offset:33024
	ds_read_b128 v[224:227], v240 offset:45312
	ds_read_b128 v[228:231], v241 offset:33024
	ds_read_b128 v[232:235], v241 offset:45312
	v_mfma_f32_32x32x16_bf16 v[66:81], v[236:239], v[98:101], v[66:81]
	s_waitcnt lgkmcnt(0)
	v_mfma_f32_32x32x16_bf16 v[82:97], v[204:207], v[134:137], v[82:97]
	v_mfma_f32_32x32x16_bf16 v[66:81], v[208:211], v[134:137], v[66:81]
	v_mfma_f32_32x32x16_bf16 v[82:97], v[212:215], v[142:145], v[82:97]
	v_mfma_f32_32x32x16_bf16 v[66:81], v[216:219], v[142:145], v[66:81]
	v_mfma_f32_32x32x16_bf16 v[82:97], v[220:223], v[130:133], v[82:97]
	v_mfma_f32_32x32x16_bf16 v[66:81], v[224:227], v[130:133], v[66:81]
	v_mfma_f32_32x32x16_bf16 v[82:97], v[228:231], v[138:141], v[82:97]
	v_mfma_f32_32x32x16_bf16 v[66:81], v[232:235], v[138:141], v[66:81]
	v_lshl_add_u32 v236, s42, 14, v196
	ds_read_b64_tr_b16 v[204:205], v236 offset:0x0
	ds_read_b64_tr_b16 v[206:207], v236 offset:0x800
	ds_read_b64_tr_b16 v[208:209], v236 offset:0x200
	ds_read_b64_tr_b16 v[210:211], v236 offset:0xa00
	ds_read_b64_tr_b16 v[212:213], v236 offset:0x400
	ds_read_b64_tr_b16 v[214:215], v236 offset:0xc00
	ds_read_b64_tr_b16 v[216:217], v236 offset:0x600
	ds_read_b64_tr_b16 v[218:219], v236 offset:0xe00
	s_nop 1
	v_max3_f32 v168, v82, v83, v84
	v_max3_f32 v168, v168, v85, v86
	v_max3_f32 v168, v168, v87, v88
	v_max3_f32 v168, v168, v89, v90
	v_max3_f32 v168, v168, v91, v92
	v_max3_f32 v168, v168, v93, v94
	v_max3_f32 v168, v168, v95, v96
	v_max3_f32 v168, v168, v97, v66
	v_max3_f32 v168, v168, v67, v68
	v_max3_f32 v168, v168, v69, v70
	v_max3_f32 v168, v168, v71, v72
	v_max3_f32 v168, v168, v73, v74
	v_max3_f32 v168, v168, v75, v76
	v_max3_f32 v168, v168, v77, v78
	v_max3_f32 v168, v168, v79, v80
	v_max_f32_e32 v168, v168, v81
	v_mov_b32_e32 v169, v168
	s_nop 1
	v_permlane32_swap_b32_e32 v168, v169
	v_max_f32_e32 v168, v168, v169
	v_sub_f32_e32 v169, v168, v199
	v_cmp_ge_f32_e32 vcc, s17, v169
	s_cmp_eq_u64 vcc, exec
	s_cbranch_scc0 .Lmy_B_slow
	v_mov_b32_e32 v168, 1.0
.Lmy_B_cont:
	v_mul_f32_e32 v238, 0xbdd53b94, v199
	ds_read_b64_tr_b16 v[220:221], v236 offset:0x1000
	ds_read_b64_tr_b16 v[222:223], v236 offset:0x1800
	ds_read_b64_tr_b16 v[224:225], v236 offset:0x1200
	ds_read_b64_tr_b16 v[226:227], v236 offset:0x1a00
	ds_read_b64_tr_b16 v[228:229], v236 offset:0x1400
	ds_read_b64_tr_b16 v[230:231], v236 offset:0x1c00
	ds_read_b64_tr_b16 v[232:233], v236 offset:0x1600
	ds_read_b64_tr_b16 v[234:235], v236 offset:0x1e00
	v_fmamk_f32 v82, v82, 0x3dd53b94, v238
	v_fmamk_f32 v83, v83, 0x3dd53b94, v238
	v_exp_f32_e32 v82, v82
	v_fmamk_f32 v84, v84, 0x3dd53b94, v238
	v_exp_f32_e32 v83, v83
	v_fmamk_f32 v85, v85, 0x3dd53b94, v238
	v_exp_f32_e32 v84, v84
	v_fmamk_f32 v86, v86, 0x3dd53b94, v238
	v_exp_f32_e32 v85, v85
	v_add_f32_e32 v237, v82, v83
	v_fmamk_f32 v87, v87, 0x3dd53b94, v238
	v_exp_f32_e32 v86, v86
	v_add_f32_e32 v237, v84, v237
	v_fmamk_f32 v88, v88, 0x3dd53b94, v238
	v_exp_f32_e32 v87, v87
	v_add_f32_e32 v237, v85, v237
	v_fmamk_f32 v89, v89, 0x3dd53b94, v238
	v_exp_f32_e32 v88, v88
	v_add_f32_e32 v237, v86, v237
	v_fmamk_f32 v90, v90, 0x3dd53b94, v238
	v_exp_f32_e32 v89, v89
	v_add_f32_e32 v237, v87, v237
	v_fmamk_f32 v91, v91, 0x3dd53b94, v238
	v_exp_f32_e32 v90, v90
	v_add_f32_e32 v237, v88, v237
	v_fmamk_f32 v92, v92, 0x3dd53b94, v238
	v_exp_f32_e32 v91, v91
	v_add_f32_e32 v237, v89, v237
	v_fmamk_f32 v93, v93, 0x3dd53b94, v238
	v_exp_f32_e32 v92, v92
; #define SBAR() __builtin_amdgcn_sched_barrier(0)
; #define RD8(KS, P) const s16x4 P##l0 = tr_read<v_rd_off(0, KS, 0)>(vb), P##h0 = tr_read<v_rd_off(0, KS, 1)>(vb), P##l1 = tr_read<v_rd_off(1, KS, 0)>(vb), P##h1 = tr_read<v_rd_off(1, KS, 1)>(vb), \
;                                P##l2 = tr_read<v_rd_off(2, KS, 0)>(vb), P##h2 = tr_read<v_rd_off(2, KS, 1)>(vb), P##l3 = tr_read<v_rd_off(3, KS, 0)>(vb), P##h3 = tr_read<v_rd_off(3, KS, 1)>(vb)
; DEVI void pv_all(f32x16 (&o)[4], int vb, bf16x8 pa0, bf16x8 pa1, bf16x8 pa2, bf16x8 pa3) {
;     ...
;   RD8(0, a); RD8(1, b);
;   asm volatile("s_waitcnt lgkmcnt(8)" ::: "memory"); SBAR(); MM4(a, pa0); SBAR();
;   RD8(2, c);
;   asm volatile("s_waitcnt lgkmcnt(8)" ::: "memory"); SBAR(); MM4(b, pa1); SBAR();
;   RD8(3, d);
;   asm volatile("s_waitcnt lgkmcnt(8)" ::: "memory"); SBAR(); MM4(c, pa2); SBAR();
;   asm volatile("s_waitcnt lgkmcnt(0)" ::: "memory"); SBAR(); MM4(d, pa3);
; template <bool ALIBI, bool LAST>
; DEVI void softmax_tile(f32x16& p0, f32x16& p1, const float C, const float nslope2, const float dbase, float& m_reg, float& l_reg, float& alpha,
;                        bf16x8& pa0, bf16x8& pa1, bf16x8& pa2, bf16x8& pa3) {
;     ...
;   {
;     const float mnC = -m_reg * C;
; #pragma unroll
;     for (int r = 0; r < 16; ++r) { p0[r] = __builtin_amdgcn_exp2f(fmaf(p0[r], C, mnC)); p1[r] = __builtin_amdgcn_exp2f(fmaf(p1[r], C, mnC)); }
;   }
;   float ps = 0.f;
; #pragma unroll
;   for (int r = 0; r < 16; ++r) ps += p0[r];
; #pragma unroll
;   for (int r = 0; r < 16; ++r) ps += p1[r];
;   { auto rr = __builtin_amdgcn_permlane32_swap(__float_as_uint(ps), __float_as_uint(ps), false, false);
;     ps = __uint_as_float(rr[0]) + __uint_as_float(rr[1]); }
;   l_reg = l_reg * alpha + ps;
;     ...
;   PK4(p0, 0, pa0); PK4(p0, 8, pa1); PK4(p1, 0, pa2); PK4(p1, 8, pa3);
	v_add_f32_e32 v237, v90, v237
	v_cvt_pk_bf16_f32 v89, v88, v89
	v_fmamk_f32 v94, v94, 0x3dd53b94, v238
	v_exp_f32_e32 v93, v93
	v_add_f32_e32 v237, v91, v237
	v_cvt_pk_bf16_f32 v88, v86, v87
	v_fmamk_f32 v95, v95, 0x3dd53b94, v238
	v_exp_f32_e32 v94, v94
	v_add_f32_e32 v237, v92, v237
	v_cvt_pk_bf16_f32 v87, v84, v85
	v_fmamk_f32 v96, v96, 0x3dd53b94, v238
	v_exp_f32_e32 v95, v95
	v_add_f32_e32 v237, v93, v237
	v_cvt_pk_bf16_f32 v86, v82, v83
	v_fmamk_f32 v97, v97, 0x3dd53b94, v238
	v_exp_f32_e32 v96, v96
	v_add_f32_e32 v237, v94, v237
	v_fmamk_f32 v66, v66, 0x3dd53b94, v238
	v_exp_f32_e32 v97, v97
	v_add_f32_e32 v237, v95, v237
	v_permlane32_swap_b32_e32 v86, v88
	v_fmamk_f32 v67, v67, 0x3dd53b94, v238
	v_exp_f32_e32 v66, v66
	v_add_f32_e32 v237, v96, v237
	v_permlane32_swap_b32_e32 v87, v89
	v_fmamk_f32 v68, v68, 0x3dd53b94, v238
	v_exp_f32_e32 v67, v67
	v_add_f32_e32 v237, v97, v237
	v_fmamk_f32 v69, v69, 0x3dd53b94, v238
	v_exp_f32_e32 v68, v68
	v_add_f32_e32 v237, v66, v237
	v_cvt_pk_bf16_f32 v97, v96, v97
	v_fmamk_f32 v70, v70, 0x3dd53b94, v238
	v_exp_f32_e32 v69, v69
	v_add_f32_e32 v237, v67, v237
	v_cvt_pk_bf16_f32 v96, v94, v95
	v_fmamk_f32 v71, v71, 0x3dd53b94, v238
	v_exp_f32_e32 v70, v70
	v_add_f32_e32 v237, v68, v237
	v_cvt_pk_bf16_f32 v95, v92, v93
	v_fmamk_f32 v72, v72, 0x3dd53b94, v238
	v_exp_f32_e32 v71, v71
	v_add_f32_e32 v237, v69, v237
	v_cvt_pk_bf16_f32 v94, v90, v91
	v_fmamk_f32 v73, v73, 0x3dd53b94, v238
	v_exp_f32_e32 v72, v72
	v_add_f32_e32 v237, v70, v237
	v_fmamk_f32 v74, v74, 0x3dd53b94, v238
	v_exp_f32_e32 v73, v73
	v_add_f32_e32 v237, v71, v237
	v_permlane32_swap_b32_e32 v94, v96
	v_fmamk_f32 v75, v75, 0x3dd53b94, v238
	v_exp_f32_e32 v74, v74
	v_add_f32_e32 v237, v72, v237
	v_permlane32_swap_b32_e32 v95, v97
	v_fmamk_f32 v76, v76, 0x3dd53b94, v238
	v_exp_f32_e32 v75, v75
	v_add_f32_e32 v237, v73, v237
	v_fmamk_f32 v77, v77, 0x3dd53b94, v238
	v_exp_f32_e32 v76, v76
	v_add_f32_e32 v237, v74, v237
	v_cvt_pk_bf16_f32 v73, v72, v73
	v_fmamk_f32 v78, v78, 0x3dd53b94, v238
	v_exp_f32_e32 v77, v77
	v_add_f32_e32 v237, v75, v237
	v_cvt_pk_bf16_f32 v72, v70, v71
	v_fmamk_f32 v79, v79, 0x3dd53b94, v238
	v_exp_f32_e32 v78, v78
	v_add_f32_e32 v237, v76, v237
	v_cvt_pk_bf16_f32 v71, v68, v69
	v_fmamk_f32 v80, v80, 0x3dd53b94, v238
	v_exp_f32_e32 v79, v79
	v_add_f32_e32 v237, v77, v237
	v_cvt_pk_bf16_f32 v70, v66, v67
	v_fmamk_f32 v81, v81, 0x3dd53b94, v238
	v_exp_f32_e32 v80, v80
	v_add_f32_e32 v237, v78, v237
	v_exp_f32_e32 v81, v81
	v_add_f32_e32 v237, v79, v237
	v_permlane32_swap_b32_e32 v70, v72
	v_add_f32_e32 v237, v80, v237
	v_permlane32_swap_b32_e32 v71, v73
	v_add_f32_e32 v237, v81, v237
	v_cvt_pk_bf16_f32 v81, v80, v81
	v_cvt_pk_bf16_f32 v80, v78, v79
	v_cvt_pk_bf16_f32 v79, v76, v77
	v_cvt_pk_bf16_f32 v78, v74, v75
	v_mov_b32_e32 v169, v237
	s_nop 1
	v_permlane32_swap_b32_e32 v237, v169
	v_permlane32_swap_b32_e32 v78, v80
	v_permlane32_swap_b32_e32 v79, v81
	v_add_f32_e32 v169, v237, v169
	v_fmac_f32_e32 v169, v149, v168
	v_mov_b32_e32 v149, v169
	s_waitcnt lgkmcnt(8)
	v_mfma_f32_32x32x16_bf16 v[2:17], v[204:207], v[86:89], v[2:17]
	v_mfma_f32_32x32x16_bf16 v[18:33], v[208:211], v[86:89], v[18:33]
	v_mfma_f32_32x32x16_bf16 v[34:49], v[212:215], v[86:89], v[34:49]
	v_mfma_f32_32x32x16_bf16 v[50:65], v[216:219], v[86:89], v[50:65]
	ds_read_b64_tr_b16 v[204:205], v236 offset:0x2000
	ds_read_b64_tr_b16 v[206:207], v236 offset:0x2800
	ds_read_b64_tr_b16 v[208:209], v236 offset:0x2200
	ds_read_b64_tr_b16 v[210:211], v236 offset:0x2a00
	ds_read_b64_tr_b16 v[212:213], v236 offset:0x2400
	ds_read_b64_tr_b16 v[214:215], v236 offset:0x2c00
	ds_read_b64_tr_b16 v[216:217], v236 offset:0x2600
	ds_read_b64_tr_b16 v[218:219], v236 offset:0x2e00
	s_waitcnt lgkmcnt(8)
	v_mfma_f32_32x32x16_bf16 v[2:17], v[220:223], v[94:97], v[2:17]
	v_mfma_f32_32x32x16_bf16 v[18:33], v[224:227], v[94:97], v[18:33]
	v_mfma_f32_32x32x16_bf16 v[34:49], v[228:231], v[94:97], v[34:49]
	v_mfma_f32_32x32x16_bf16 v[50:65], v[232:235], v[94:97], v[50:65]
	ds_read_b64_tr_b16 v[220:221], v236 offset:0x3000
	ds_read_b64_tr_b16 v[222:223], v236 offset:0x3800
	ds_read_b64_tr_b16 v[224:225], v236 offset:0x3200
	ds_read_b64_tr_b16 v[226:227], v236 offset:0x3a00
	ds_read_b64_tr_b16 v[228:229], v236 offset:0x3400
	ds_read_b64_tr_b16 v[230:231], v236 offset:0x3c00
	ds_read_b64_tr_b16 v[232:233], v236 offset:0x3600
	ds_read_b64_tr_b16 v[234:235], v236 offset:0x3e00
	s_waitcnt lgkmcnt(8)
	v_mfma_f32_32x32x16_bf16 v[2:17], v[204:207], v[70:73], v[2:17]
	v_mfma_f32_32x32x16_bf16 v[18:33], v[208:211], v[70:73], v[18:33]
	v_mfma_f32_32x32x16_bf16 v[34:49], v[212:215], v[70:73], v[34:49]
	v_mfma_f32_32x32x16_bf16 v[50:65], v[216:219], v[70:73], v[50:65]
	s_waitcnt lgkmcnt(0)
	v_mfma_f32_32x32x16_bf16 v[2:17], v[220:223], v[78:81], v[2:17]
	v_mfma_f32_32x32x16_bf16 v[18:33], v[224:227], v[78:81], v[18:33]
	v_mfma_f32_32x32x16_bf16 v[34:49], v[228:231], v[78:81], v[34:49]
	v_mfma_f32_32x32x16_bf16 v[50:65], v[232:235], v[78:81], v[50:65]
	s_branch .LBB0_210
; template <bool ALIBI, bool LAST>
; DEVI void softmax_tile(f32x16& p0, f32x16& p1, const float C, const float nslope2, const float dbase, float& m_reg, float& l_reg, float& alpha,
;                        bf16x8& pa0, bf16x8& pa1, bf16x8& pa2, bf16x8& pa3) {
;     ...
;   if (__builtin_expect(__all(pmax - m_reg <= THRU), 1)) { alpha = 1.f; }
;   else { float mn = fmaxf(m_reg, pmax); alpha = __builtin_amdgcn_exp2f((m_reg - mn) * CU); m_reg = mn; }
; template <int DQK, bool ALIBI>
; DEVI void attn_pass(const AttnArgs& a, f32x16 (&o)[4], const int tid_) {
;     ...
;       if (__any(alpha < 1.f)) {
; #pragma unroll
;         for (int d = 0; d < 4; ++d)
; #pragma unroll
;           for (int r = 0; r < 16; ++r) o[d][r] *= alpha;
;       }
.Lmy_B_slow:
	v_max_f32_e32 v169, v199, v199
	v_max_f32_e32 v168, v169, v168
	v_sub_f32_e32 v169, v199, v168
	v_mul_f32_e32 v169, 0x3dd53b94, v169
	v_exp_f32_e32 v169, v169
	v_mov_b32_e32 v199, v168
	v_mov_b32_e32 v168, v169
	v_cmp_gt_f32_e32 vcc, 1.0, v168
	s_cbranch_vccz .Lmy_B_cont
	v_pk_mul_f32 v[16:17], v[16:17], v[168:169] op_sel_hi:[1,0]
	v_pk_mul_f32 v[14:15], v[14:15], v[168:169] op_sel_hi:[1,0]
	v_pk_mul_f32 v[12:13], v[12:13], v[168:169] op_sel_hi:[1,0]
	v_pk_mul_f32 v[10:11], v[10:11], v[168:169] op_sel_hi:[1,0]
	v_pk_mul_f32 v[8:9], v[8:9], v[168:169] op_sel_hi:[1,0]
	v_pk_mul_f32 v[6:7], v[6:7], v[168:169] op_sel_hi:[1,0]
	v_pk_mul_f32 v[4:5], v[4:5], v[168:169] op_sel_hi:[1,0]
	v_pk_mul_f32 v[2:3], v[2:3], v[168:169] op_sel_hi:[1,0]
	v_pk_mul_f32 v[32:33], v[32:33], v[168:169] op_sel_hi:[1,0]
	v_pk_mul_f32 v[30:31], v[30:31], v[168:169] op_sel_hi:[1,0]
	v_pk_mul_f32 v[28:29], v[28:29], v[168:169] op_sel_hi:[1,0]
	v_pk_mul_f32 v[26:27], v[26:27], v[168:169] op_sel_hi:[1,0]
	v_pk_mul_f32 v[24:25], v[24:25], v[168:169] op_sel_hi:[1,0]
	v_pk_mul_f32 v[22:23], v[22:23], v[168:169] op_sel_hi:[1,0]
	v_pk_mul_f32 v[20:21], v[20:21], v[168:169] op_sel_hi:[1,0]
	v_pk_mul_f32 v[18:19], v[18:19], v[168:169] op_sel_hi:[1,0]
	v_pk_mul_f32 v[48:49], v[48:49], v[168:169] op_sel_hi:[1,0]
	v_pk_mul_f32 v[46:47], v[46:47], v[168:169] op_sel_hi:[1,0]
	v_pk_mul_f32 v[44:45], v[44:45], v[168:169] op_sel_hi:[1,0]
	v_pk_mul_f32 v[42:43], v[42:43], v[168:169] op_sel_hi:[1,0]
	v_pk_mul_f32 v[40:41], v[40:41], v[168:169] op_sel_hi:[1,0]
	v_pk_mul_f32 v[38:39], v[38:39], v[168:169] op_sel_hi:[1,0]
	v_pk_mul_f32 v[36:37], v[36:37], v[168:169] op_sel_hi:[1,0]
	v_pk_mul_f32 v[34:35], v[34:35], v[168:169] op_sel_hi:[1,0]
	v_pk_mul_f32 v[64:65], v[64:65], v[168:169] op_sel_hi:[1,0]
	v_pk_mul_f32 v[62:63], v[62:63], v[168:169] op_sel_hi:[1,0]
	v_pk_mul_f32 v[60:61], v[60:61], v[168:169] op_sel_hi:[1,0]
	v_pk_mul_f32 v[58:59], v[58:59], v[168:169] op_sel_hi:[1,0]
	v_pk_mul_f32 v[56:57], v[56:57], v[168:169] op_sel_hi:[1,0]
	v_pk_mul_f32 v[54:55], v[54:55], v[168:169] op_sel_hi:[1,0]
	v_pk_mul_f32 v[52:53], v[52:53], v[168:169] op_sel_hi:[1,0]
	v_pk_mul_f32 v[50:51], v[50:51], v[168:169] op_sel_hi:[1,0]
	s_branch .Lmy_B_cont
